# accumulators cleared once per tile (zero-trip test first) instead of twice, on top of EpiResid prefetch
# baseline (speedup 1.0000x reference)
; template <class Epi, class Sched, bool ALIGN_EPI = false, bool SP2 = false>
; __device__ __forceinline__ void gemm_phase(PG8_LAS unsigned char* lds, const Gemm g, const Sched& S, const Epi& E, int tid_in) {
;     ...
;         for (int t = 0; t < nt; t += 2) {
;     ...
;         for (int a = 0; a < 2; ++a)
; #pragma unroll
;             for (int b = 0; b < 2; ++b)
; #pragma unroll
;                 for (int m = 0; m < 4; ++m)
; #pragma unroll
;                     for (int n = 0; n < 2; ++n) acc[a][b][m][n] = (f32x4){0.f, 0.f, 0.f, 0.f};
.LBB0_186:
	s_andn2_b64 vcc, exec, s[24:25]
	s_cbranch_vccz .Lkeep_acc_1
	v_mov_b32_e32 v127, 0
	v_mov_b32_e32 v126, v127
	v_mov_b32_e32 v125, v127
	v_mov_b32_e32 v124, v127
	v_mov_b32_e32 v123, v127
	v_mov_b32_e32 v122, v127
	v_mov_b32_e32 v121, v127
	v_mov_b32_e32 v120, v127
	v_mov_b32_e32 v111, v127
	v_mov_b32_e32 v110, v127
	v_mov_b32_e32 v109, v127
	v_mov_b32_e32 v108, v127
	v_mov_b32_e32 v107, v127
	v_mov_b32_e32 v106, v127
	v_mov_b32_e32 v105, v127
	v_mov_b32_e32 v104, v127
	v_mov_b32_e32 v95, v127
	v_mov_b32_e32 v94, v127
	v_mov_b32_e32 v93, v127
	v_mov_b32_e32 v92, v127
	v_mov_b32_e32 v91, v127
	v_mov_b32_e32 v90, v127
	v_mov_b32_e32 v89, v127
	v_mov_b32_e32 v88, v127
	v_mov_b32_e32 v79, v127
	v_mov_b32_e32 v78, v127
	v_mov_b32_e32 v77, v127
	v_mov_b32_e32 v76, v127
	v_mov_b32_e32 v75, v127
	v_mov_b32_e32 v74, v127
	v_mov_b32_e32 v73, v127
	v_mov_b32_e32 v72, v127
	v_mov_b32_e32 v119, v127
	v_mov_b32_e32 v118, v127
	v_mov_b32_e32 v117, v127
	v_mov_b32_e32 v116, v127
	v_mov_b32_e32 v115, v127
	v_mov_b32_e32 v114, v127
	v_mov_b32_e32 v113, v127
	v_mov_b32_e32 v112, v127
	v_mov_b32_e32 v103, v127
	v_mov_b32_e32 v102, v127
	v_mov_b32_e32 v101, v127
	v_mov_b32_e32 v100, v127
	v_mov_b32_e32 v99, v127
	v_mov_b32_e32 v98, v127
	v_mov_b32_e32 v97, v127
	v_mov_b32_e32 v96, v127
	v_mov_b32_e32 v87, v127
	v_mov_b32_e32 v86, v127
	v_mov_b32_e32 v85, v127
	v_mov_b32_e32 v84, v127
	v_mov_b32_e32 v83, v127
	v_mov_b32_e32 v82, v127
	v_mov_b32_e32 v81, v127
	v_mov_b32_e32 v80, v127
	v_mov_b32_e32 v71, v127
	v_mov_b32_e32 v70, v127
	v_mov_b32_e32 v69, v127
	v_mov_b32_e32 v68, v127
	v_mov_b32_e32 v67, v127
	v_mov_b32_e32 v66, v127
	v_mov_b32_e32 v65, v127
	v_mov_b32_e32 v64, v127
	v_mov_b32_e32 v63, v127
	v_mov_b32_e32 v62, v127
	v_mov_b32_e32 v61, v127
	v_mov_b32_e32 v60, v127
	v_mov_b32_e32 v59, v127
	v_mov_b32_e32 v58, v127
	v_mov_b32_e32 v57, v127
	v_mov_b32_e32 v56, v127
	v_mov_b32_e32 v47, v127
	v_mov_b32_e32 v46, v127
	v_mov_b32_e32 v45, v127
	v_mov_b32_e32 v44, v127
	v_mov_b32_e32 v43, v127
	v_mov_b32_e32 v42, v127
	v_mov_b32_e32 v41, v127
	v_mov_b32_e32 v40, v127
	v_mov_b32_e32 v31, v127
	v_mov_b32_e32 v30, v127
	v_mov_b32_e32 v29, v127
	v_mov_b32_e32 v28, v127
	v_mov_b32_e32 v27, v127
	v_mov_b32_e32 v26, v127
	v_mov_b32_e32 v25, v127
	v_mov_b32_e32 v24, v127
	v_mov_b32_e32 v15, v127
	v_mov_b32_e32 v14, v127
	v_mov_b32_e32 v13, v127
	v_mov_b32_e32 v12, v127
	v_mov_b32_e32 v11, v127
	v_mov_b32_e32 v10, v127
	v_mov_b32_e32 v9, v127
	v_mov_b32_e32 v8, v127
	v_mov_b32_e32 v55, v127
	v_mov_b32_e32 v54, v127
	v_mov_b32_e32 v53, v127
	v_mov_b32_e32 v52, v127
	v_mov_b32_e32 v51, v127
	v_mov_b32_e32 v50, v127
	v_mov_b32_e32 v49, v127
	v_mov_b32_e32 v48, v127
	v_mov_b32_e32 v39, v127
	v_mov_b32_e32 v38, v127
	v_mov_b32_e32 v37, v127
	v_mov_b32_e32 v36, v127
	v_mov_b32_e32 v35, v127
	v_mov_b32_e32 v34, v127
	v_mov_b32_e32 v33, v127
	v_mov_b32_e32 v32, v127
	v_mov_b32_e32 v23, v127
	v_mov_b32_e32 v22, v127
	v_mov_b32_e32 v21, v127
	v_mov_b32_e32 v20, v127
	v_mov_b32_e32 v19, v127
	v_mov_b32_e32 v18, v127
	v_mov_b32_e32 v17, v127
	v_mov_b32_e32 v16, v127
	v_mov_b32_e32 v7, v127
	v_mov_b32_e32 v6, v127
	v_mov_b32_e32 v5, v127
	v_mov_b32_e32 v4, v127
	v_mov_b32_e32 v3, v127
	v_mov_b32_e32 v2, v127
	v_mov_b32_e32 v1, v127
	v_mov_b32_e32 v0, v127
	s_branch .LBB0_189
.Lkeep_acc_1:
	s_add_u32 s38, s38, 0x80
	s_addc_u32 s39, s39, 0
	s_add_u32 s81, s40, 0x100
	v_mov_b32_e32 v0, 0
	s_addc_u32 s83, s41, 0
	s_mov_b32 s40, 0
	v_mov_b32_e32 v1, v0
	v_mov_b32_e32 v2, v0
	v_mov_b32_e32 v3, v0
	v_mov_b32_e32 v4, v0
	v_mov_b32_e32 v5, v0
	v_mov_b32_e32 v6, v0
	v_mov_b32_e32 v7, v0
	v_mov_b32_e32 v16, v0
	v_mov_b32_e32 v17, v0
	v_mov_b32_e32 v18, v0
	v_mov_b32_e32 v19, v0
	v_mov_b32_e32 v20, v0
	v_mov_b32_e32 v21, v0
	v_mov_b32_e32 v22, v0
	v_mov_b32_e32 v23, v0
	v_mov_b32_e32 v32, v0
	v_mov_b32_e32 v33, v0
	v_mov_b32_e32 v34, v0
	v_mov_b32_e32 v35, v0
	v_mov_b32_e32 v36, v0
	v_mov_b32_e32 v37, v0
	v_mov_b32_e32 v38, v0
	v_mov_b32_e32 v39, v0
	v_mov_b32_e32 v48, v0
	v_mov_b32_e32 v49, v0
	v_mov_b32_e32 v50, v0
	v_mov_b32_e32 v51, v0
	v_mov_b32_e32 v52, v0
	v_mov_b32_e32 v53, v0
	v_mov_b32_e32 v54, v0
	v_mov_b32_e32 v55, v0
	v_mov_b32_e32 v8, v0
	v_mov_b32_e32 v9, v0
	v_mov_b32_e32 v10, v0
	v_mov_b32_e32 v11, v0
	v_mov_b32_e32 v12, v0
	v_mov_b32_e32 v13, v0
	v_mov_b32_e32 v14, v0
	v_mov_b32_e32 v15, v0
	v_mov_b32_e32 v24, v0
	v_mov_b32_e32 v25, v0
	v_mov_b32_e32 v26, v0
	v_mov_b32_e32 v27, v0
	v_mov_b32_e32 v28, v0
	v_mov_b32_e32 v29, v0
	v_mov_b32_e32 v30, v0
	v_mov_b32_e32 v31, v0
	v_mov_b32_e32 v40, v0
	v_mov_b32_e32 v41, v0
	v_mov_b32_e32 v42, v0
	v_mov_b32_e32 v43, v0
	v_mov_b32_e32 v44, v0
	v_mov_b32_e32 v45, v0
	v_mov_b32_e32 v46, v0
	v_mov_b32_e32 v47, v0
	v_mov_b32_e32 v56, v0
	v_mov_b32_e32 v57, v0
	v_mov_b32_e32 v58, v0
	v_mov_b32_e32 v59, v0
	v_mov_b32_e32 v60, v0
	v_mov_b32_e32 v61, v0
	v_mov_b32_e32 v62, v0
	v_mov_b32_e32 v63, v0
	v_mov_b32_e32 v64, v0
	v_mov_b32_e32 v65, v0
	v_mov_b32_e32 v66, v0
	v_mov_b32_e32 v67, v0
	v_mov_b32_e32 v68, v0
	v_mov_b32_e32 v69, v0
	v_mov_b32_e32 v70, v0
	v_mov_b32_e32 v71, v0
	v_mov_b32_e32 v80, v0
	v_mov_b32_e32 v81, v0
	v_mov_b32_e32 v82, v0
	v_mov_b32_e32 v83, v0
	v_mov_b32_e32 v84, v0
	v_mov_b32_e32 v85, v0
	v_mov_b32_e32 v86, v0
	v_mov_b32_e32 v87, v0
	v_mov_b32_e32 v96, v0
	v_mov_b32_e32 v97, v0
	v_mov_b32_e32 v98, v0
	v_mov_b32_e32 v99, v0
	v_mov_b32_e32 v100, v0
	v_mov_b32_e32 v101, v0
	v_mov_b32_e32 v102, v0
	v_mov_b32_e32 v103, v0
	v_mov_b32_e32 v112, v0
	v_mov_b32_e32 v113, v0
	v_mov_b32_e32 v114, v0
	v_mov_b32_e32 v115, v0
	v_mov_b32_e32 v116, v0
	v_mov_b32_e32 v117, v0
	v_mov_b32_e32 v118, v0
	v_mov_b32_e32 v119, v0
	v_mov_b32_e32 v72, v0
	v_mov_b32_e32 v73, v0
	v_mov_b32_e32 v74, v0
	v_mov_b32_e32 v75, v0
	v_mov_b32_e32 v76, v0
	v_mov_b32_e32 v77, v0
	v_mov_b32_e32 v78, v0
	v_mov_b32_e32 v79, v0
	v_mov_b32_e32 v88, v0
	v_mov_b32_e32 v89, v0
	v_mov_b32_e32 v90, v0
	v_mov_b32_e32 v91, v0
	v_mov_b32_e32 v92, v0
	v_mov_b32_e32 v93, v0
	v_mov_b32_e32 v94, v0
	v_mov_b32_e32 v95, v0
	v_mov_b32_e32 v104, v0
	v_mov_b32_e32 v105, v0
	v_mov_b32_e32 v106, v0
	v_mov_b32_e32 v107, v0
	v_mov_b32_e32 v108, v0
	v_mov_b32_e32 v109, v0
	v_mov_b32_e32 v110, v0
	v_mov_b32_e32 v111, v0
	v_mov_b32_e32 v120, v0
	v_mov_b32_e32 v121, v0
	v_mov_b32_e32 v122, v0
	v_mov_b32_e32 v123, v0
	v_mov_b32_e32 v124, v0
	v_mov_b32_e32 v125, v0
	v_mov_b32_e32 v126, v0
	v_mov_b32_e32 v127, v0

; template <class Epi, class Sched, bool ALIGN_EPI = false, bool SP2 = false>
; __device__ __forceinline__ void gemm_phase(PG8_LAS unsigned char* lds, const Gemm g, const Sched& S, const Epi& E, int tid_in) {
;     ...
;         for (int t = 0; t < nt; t += 2) {
;     ...
;         for (int a = 0; a < 2; ++a)
; #pragma unroll
;             for (int b = 0; b < 2; ++b)
; #pragma unroll
;                 for (int m = 0; m < 4; ++m)
; #pragma unroll
;                     for (int n = 0; n < 2; ++n) acc[a][b][m][n] = (f32x4){0.f, 0.f, 0.f, 0.f};
.LBB0_363:
	s_andn2_b64 vcc, exec, s[40:41]
	s_cbranch_vccz .Lkeep_acc_2
	v_mov_b32_e32 v123, 0
	v_mov_b32_e32 v122, v123
	v_mov_b32_e32 v121, v123
	v_mov_b32_e32 v120, v123
	v_mov_b32_e32 v127, v123
	v_mov_b32_e32 v126, v123
	v_mov_b32_e32 v125, v123
	v_mov_b32_e32 v124, v123
	v_mov_b32_e32 v111, v123
	v_mov_b32_e32 v110, v123
	v_mov_b32_e32 v109, v123
	v_mov_b32_e32 v108, v123
	v_mov_b32_e32 v107, v123
	v_mov_b32_e32 v106, v123
	v_mov_b32_e32 v105, v123
	v_mov_b32_e32 v104, v123
	v_mov_b32_e32 v95, v123
	v_mov_b32_e32 v94, v123
	v_mov_b32_e32 v93, v123
	v_mov_b32_e32 v92, v123
	v_mov_b32_e32 v91, v123
	v_mov_b32_e32 v90, v123
	v_mov_b32_e32 v89, v123
	v_mov_b32_e32 v88, v123
	v_mov_b32_e32 v79, v123
	v_mov_b32_e32 v78, v123
	v_mov_b32_e32 v77, v123
	v_mov_b32_e32 v76, v123
	v_mov_b32_e32 v75, v123
	v_mov_b32_e32 v74, v123
	v_mov_b32_e32 v73, v123
	v_mov_b32_e32 v72, v123
	v_mov_b32_e32 v119, v123
	v_mov_b32_e32 v118, v123
	v_mov_b32_e32 v117, v123
	v_mov_b32_e32 v116, v123
	v_mov_b32_e32 v115, v123
	v_mov_b32_e32 v114, v123
	v_mov_b32_e32 v113, v123
	v_mov_b32_e32 v112, v123
	v_mov_b32_e32 v103, v123
	v_mov_b32_e32 v102, v123
	v_mov_b32_e32 v101, v123
	v_mov_b32_e32 v100, v123
	v_mov_b32_e32 v99, v123
	v_mov_b32_e32 v98, v123
	v_mov_b32_e32 v97, v123
	v_mov_b32_e32 v96, v123
	v_mov_b32_e32 v87, v123
	v_mov_b32_e32 v86, v123
	v_mov_b32_e32 v85, v123
	v_mov_b32_e32 v84, v123
	v_mov_b32_e32 v83, v123
	v_mov_b32_e32 v82, v123
	v_mov_b32_e32 v81, v123
	v_mov_b32_e32 v80, v123
	v_mov_b32_e32 v71, v123
	v_mov_b32_e32 v70, v123
	v_mov_b32_e32 v69, v123
	v_mov_b32_e32 v68, v123
	v_mov_b32_e32 v67, v123
	v_mov_b32_e32 v66, v123
	v_mov_b32_e32 v65, v123
	v_mov_b32_e32 v64, v123
	v_mov_b32_e32 v63, v123
	v_mov_b32_e32 v62, v123
	v_mov_b32_e32 v61, v123
	v_mov_b32_e32 v60, v123
	v_mov_b32_e32 v59, v123
	v_mov_b32_e32 v58, v123
	v_mov_b32_e32 v57, v123
	v_mov_b32_e32 v56, v123
	v_mov_b32_e32 v47, v123
	v_mov_b32_e32 v46, v123
	v_mov_b32_e32 v45, v123
	v_mov_b32_e32 v44, v123
	v_mov_b32_e32 v43, v123
	v_mov_b32_e32 v42, v123
	v_mov_b32_e32 v41, v123
	v_mov_b32_e32 v40, v123
	v_mov_b32_e32 v31, v123
	v_mov_b32_e32 v30, v123
	v_mov_b32_e32 v29, v123
	v_mov_b32_e32 v28, v123
	v_mov_b32_e32 v27, v123
	v_mov_b32_e32 v26, v123
	v_mov_b32_e32 v25, v123
	v_mov_b32_e32 v24, v123
	v_mov_b32_e32 v15, v123
	v_mov_b32_e32 v14, v123
	v_mov_b32_e32 v13, v123
	v_mov_b32_e32 v12, v123
	v_mov_b32_e32 v11, v123
	v_mov_b32_e32 v10, v123
	v_mov_b32_e32 v9, v123
	v_mov_b32_e32 v8, v123
	v_mov_b32_e32 v55, v123
	v_mov_b32_e32 v54, v123
	v_mov_b32_e32 v53, v123
	v_mov_b32_e32 v52, v123
	v_mov_b32_e32 v51, v123
	v_mov_b32_e32 v50, v123
	v_mov_b32_e32 v49, v123
	v_mov_b32_e32 v48, v123
	v_mov_b32_e32 v39, v123
	v_mov_b32_e32 v38, v123
	v_mov_b32_e32 v37, v123
	v_mov_b32_e32 v36, v123
	v_mov_b32_e32 v35, v123
	v_mov_b32_e32 v34, v123
	v_mov_b32_e32 v33, v123
	v_mov_b32_e32 v32, v123
	v_mov_b32_e32 v23, v123
	v_mov_b32_e32 v22, v123
	v_mov_b32_e32 v21, v123
	v_mov_b32_e32 v20, v123
	v_mov_b32_e32 v19, v123
	v_mov_b32_e32 v18, v123
	v_mov_b32_e32 v17, v123
	v_mov_b32_e32 v16, v123
	v_mov_b32_e32 v7, v123
	v_mov_b32_e32 v6, v123
	v_mov_b32_e32 v5, v123
	v_mov_b32_e32 v4, v123
	v_mov_b32_e32 v3, v123
	v_mov_b32_e32 v2, v123
	v_mov_b32_e32 v1, v123
	v_mov_b32_e32 v0, v123
	s_branch .LBB0_366
.Lkeep_acc_2:
	s_add_u32 s4, s8, 0x80
	s_addc_u32 s5, s9, 0
	s_add_u32 s8, s6, 0x100
	v_mov_b32_e32 v0, 0
	s_addc_u32 s9, s7, 0
	s_mov_b32 s6, 0
	v_mov_b32_e32 v1, v0
	v_mov_b32_e32 v2, v0
	v_mov_b32_e32 v3, v0
	v_mov_b32_e32 v4, v0
	v_mov_b32_e32 v5, v0
	v_mov_b32_e32 v6, v0
	v_mov_b32_e32 v7, v0
	v_mov_b32_e32 v16, v0
	v_mov_b32_e32 v17, v0
	v_mov_b32_e32 v18, v0
	v_mov_b32_e32 v19, v0
	v_mov_b32_e32 v20, v0
	v_mov_b32_e32 v21, v0
	v_mov_b32_e32 v22, v0
	v_mov_b32_e32 v23, v0
	v_mov_b32_e32 v32, v0
	v_mov_b32_e32 v33, v0
	v_mov_b32_e32 v34, v0
	v_mov_b32_e32 v35, v0
	v_mov_b32_e32 v36, v0
	v_mov_b32_e32 v37, v0
	v_mov_b32_e32 v38, v0
	v_mov_b32_e32 v39, v0
	v_mov_b32_e32 v48, v0
	v_mov_b32_e32 v49, v0
	v_mov_b32_e32 v50, v0
	v_mov_b32_e32 v51, v0
	v_mov_b32_e32 v52, v0
	v_mov_b32_e32 v53, v0
	v_mov_b32_e32 v54, v0
	v_mov_b32_e32 v55, v0
	v_mov_b32_e32 v8, v0
	v_mov_b32_e32 v9, v0
	v_mov_b32_e32 v10, v0
	v_mov_b32_e32 v11, v0
	v_mov_b32_e32 v12, v0
	v_mov_b32_e32 v13, v0
	v_mov_b32_e32 v14, v0
	v_mov_b32_e32 v15, v0
	v_mov_b32_e32 v24, v0
	v_mov_b32_e32 v25, v0
	v_mov_b32_e32 v26, v0
	v_mov_b32_e32 v27, v0
	v_mov_b32_e32 v28, v0
	v_mov_b32_e32 v29, v0
	v_mov_b32_e32 v30, v0
	v_mov_b32_e32 v31, v0
	v_mov_b32_e32 v40, v0
	v_mov_b32_e32 v41, v0
	v_mov_b32_e32 v42, v0
	v_mov_b32_e32 v43, v0
	v_mov_b32_e32 v44, v0
	v_mov_b32_e32 v45, v0
	v_mov_b32_e32 v46, v0
	v_mov_b32_e32 v47, v0
	v_mov_b32_e32 v56, v0
	v_mov_b32_e32 v57, v0
	v_mov_b32_e32 v58, v0
	v_mov_b32_e32 v59, v0
	v_mov_b32_e32 v60, v0
	v_mov_b32_e32 v61, v0
	v_mov_b32_e32 v62, v0
	v_mov_b32_e32 v63, v0
	v_mov_b32_e32 v64, v0
	v_mov_b32_e32 v65, v0
	v_mov_b32_e32 v66, v0
	v_mov_b32_e32 v67, v0
	v_mov_b32_e32 v68, v0
	v_mov_b32_e32 v69, v0
	v_mov_b32_e32 v70, v0
	v_mov_b32_e32 v71, v0
	v_mov_b32_e32 v80, v0
	v_mov_b32_e32 v81, v0
	v_mov_b32_e32 v82, v0
	v_mov_b32_e32 v83, v0
	v_mov_b32_e32 v84, v0
	v_mov_b32_e32 v85, v0
	v_mov_b32_e32 v86, v0
	v_mov_b32_e32 v87, v0
	v_mov_b32_e32 v96, v0
	v_mov_b32_e32 v97, v0
	v_mov_b32_e32 v98, v0
	v_mov_b32_e32 v99, v0
	v_mov_b32_e32 v100, v0
	v_mov_b32_e32 v101, v0
	v_mov_b32_e32 v102, v0
	v_mov_b32_e32 v103, v0
	v_mov_b32_e32 v112, v0
	v_mov_b32_e32 v113, v0
	v_mov_b32_e32 v114, v0
	v_mov_b32_e32 v115, v0
	v_mov_b32_e32 v116, v0
	v_mov_b32_e32 v117, v0
	v_mov_b32_e32 v118, v0
	v_mov_b32_e32 v119, v0
	v_mov_b32_e32 v72, v0
	v_mov_b32_e32 v73, v0
	v_mov_b32_e32 v74, v0
	v_mov_b32_e32 v75, v0
	v_mov_b32_e32 v76, v0
	v_mov_b32_e32 v77, v0
	v_mov_b32_e32 v78, v0
	v_mov_b32_e32 v79, v0
	v_mov_b32_e32 v88, v0
	v_mov_b32_e32 v89, v0
	v_mov_b32_e32 v90, v0
	v_mov_b32_e32 v91, v0
	v_mov_b32_e32 v92, v0
	v_mov_b32_e32 v93, v0
	v_mov_b32_e32 v94, v0
	v_mov_b32_e32 v95, v0
	v_mov_b32_e32 v104, v0
	v_mov_b32_e32 v105, v0
	v_mov_b32_e32 v106, v0
	v_mov_b32_e32 v107, v0
	v_mov_b32_e32 v108, v0
	v_mov_b32_e32 v109, v0
	v_mov_b32_e32 v110, v0
	v_mov_b32_e32 v111, v0
	v_mov_b32_e32 v124, v0
	v_mov_b32_e32 v125, v0
	v_mov_b32_e32 v126, v0
	v_mov_b32_e32 v127, v0
	v_mov_b32_e32 v120, v0
	v_mov_b32_e32 v121, v0
	v_mov_b32_e32 v122, v0
	v_mov_b32_e32 v123, v0

; template <class Epi, class Sched, bool ALIGN_EPI = false, bool SP2 = false>
; __device__ __forceinline__ void gemm_phase(PG8_LAS unsigned char* lds, const Gemm g, const Sched& S, const Epi& E, int tid_in) {
;     ...
;         for (int t = 0; t < nt; t += 2) {
;     ...
;         for (int a = 0; a < 2; ++a)
; #pragma unroll
;             for (int b = 0; b < 2; ++b)
; #pragma unroll
;                 for (int m = 0; m < 4; ++m)
; #pragma unroll
;                     for (int n = 0; n < 2; ++n) acc[a][b][m][n] = (f32x4){0.f, 0.f, 0.f, 0.f};
.LBB0_989:
	s_andn2_b64 vcc, exec, s[36:37]
	s_cbranch_vccz .Lkeep_acc_3
	v_mov_b32_e32 v135, 0
	v_mov_b32_e32 v134, v135
	v_mov_b32_e32 v133, v135
	v_mov_b32_e32 v132, v135
	v_mov_b32_e32 v131, v135
	v_mov_b32_e32 v130, v135
	v_mov_b32_e32 v129, v135
	v_mov_b32_e32 v128, v135
	v_mov_b32_e32 v127, v135
	v_mov_b32_e32 v126, v135
	v_mov_b32_e32 v125, v135
	v_mov_b32_e32 v124, v135
	v_mov_b32_e32 v123, v135
	v_mov_b32_e32 v122, v135
	v_mov_b32_e32 v121, v135
	v_mov_b32_e32 v120, v135
	v_mov_b32_e32 v119, v135
	v_mov_b32_e32 v118, v135
	v_mov_b32_e32 v117, v135
	v_mov_b32_e32 v116, v135
	v_mov_b32_e32 v115, v135
	v_mov_b32_e32 v114, v135
	v_mov_b32_e32 v113, v135
	v_mov_b32_e32 v112, v135
	v_mov_b32_e32 v111, v135
	v_mov_b32_e32 v110, v135
	v_mov_b32_e32 v109, v135
	v_mov_b32_e32 v108, v135
	v_mov_b32_e32 v103, v135
	v_mov_b32_e32 v102, v135
	v_mov_b32_e32 v101, v135
	v_mov_b32_e32 v100, v135
	v_mov_b32_e32 v63, v135
	v_mov_b32_e32 v62, v135
	v_mov_b32_e32 v61, v135
	v_mov_b32_e32 v60, v135
	v_mov_b32_e32 v59, v135
	v_mov_b32_e32 v58, v135
	v_mov_b32_e32 v57, v135
	v_mov_b32_e32 v56, v135
	v_mov_b32_e32 v55, v135
	v_mov_b32_e32 v54, v135
	v_mov_b32_e32 v53, v135
	v_mov_b32_e32 v52, v135
	v_mov_b32_e32 v51, v135
	v_mov_b32_e32 v50, v135
	v_mov_b32_e32 v49, v135
	v_mov_b32_e32 v48, v135
	v_mov_b32_e32 v47, v135
	v_mov_b32_e32 v46, v135
	v_mov_b32_e32 v45, v135
	v_mov_b32_e32 v44, v135
	v_mov_b32_e32 v43, v135
	v_mov_b32_e32 v42, v135
	v_mov_b32_e32 v41, v135
	v_mov_b32_e32 v40, v135
	v_mov_b32_e32 v39, v135
	v_mov_b32_e32 v38, v135
	v_mov_b32_e32 v37, v135
	v_mov_b32_e32 v36, v135
	v_mov_b32_e32 v35, v135
	v_mov_b32_e32 v34, v135
	v_mov_b32_e32 v33, v135
	v_mov_b32_e32 v32, v135
	v_mov_b32_e32 v95, v135
	v_mov_b32_e32 v94, v135
	v_mov_b32_e32 v93, v135
	v_mov_b32_e32 v92, v135
	v_mov_b32_e32 v91, v135
	v_mov_b32_e32 v90, v135
	v_mov_b32_e32 v89, v135
	v_mov_b32_e32 v88, v135
	v_mov_b32_e32 v87, v135
	v_mov_b32_e32 v86, v135
	v_mov_b32_e32 v85, v135
	v_mov_b32_e32 v84, v135
	v_mov_b32_e32 v83, v135
	v_mov_b32_e32 v82, v135
	v_mov_b32_e32 v81, v135
	v_mov_b32_e32 v80, v135
	v_mov_b32_e32 v79, v135
	v_mov_b32_e32 v78, v135
	v_mov_b32_e32 v77, v135
	v_mov_b32_e32 v76, v135
	v_mov_b32_e32 v75, v135
	v_mov_b32_e32 v74, v135
	v_mov_b32_e32 v73, v135
	v_mov_b32_e32 v72, v135
	v_mov_b32_e32 v71, v135
	v_mov_b32_e32 v70, v135
	v_mov_b32_e32 v69, v135
	v_mov_b32_e32 v68, v135
	v_mov_b32_e32 v67, v135
	v_mov_b32_e32 v66, v135
	v_mov_b32_e32 v65, v135
	v_mov_b32_e32 v64, v135
	v_mov_b32_e32 v31, v135
	v_mov_b32_e32 v30, v135
	v_mov_b32_e32 v29, v135
	v_mov_b32_e32 v28, v135
	v_mov_b32_e32 v27, v135
	v_mov_b32_e32 v26, v135
	v_mov_b32_e32 v25, v135
	v_mov_b32_e32 v24, v135
	v_mov_b32_e32 v23, v135
	v_mov_b32_e32 v22, v135
	v_mov_b32_e32 v21, v135
	v_mov_b32_e32 v20, v135
	v_mov_b32_e32 v19, v135
	v_mov_b32_e32 v18, v135
	v_mov_b32_e32 v17, v135
	v_mov_b32_e32 v16, v135
	v_mov_b32_e32 v15, v135
	v_mov_b32_e32 v14, v135
	v_mov_b32_e32 v13, v135
	v_mov_b32_e32 v12, v135
	v_mov_b32_e32 v11, v135
	v_mov_b32_e32 v10, v135
	v_mov_b32_e32 v9, v135
	v_mov_b32_e32 v8, v135
	v_mov_b32_e32 v7, v135
	v_mov_b32_e32 v6, v135
	v_mov_b32_e32 v5, v135
	v_mov_b32_e32 v4, v135
	v_mov_b32_e32 v3, v135
	v_mov_b32_e32 v2, v135
	v_mov_b32_e32 v1, v135
	v_mov_b32_e32 v0, v135
	s_branch .LBB0_993
.Lkeep_acc_3:
	s_add_u32 s4, s40, 0x80
	s_addc_u32 s5, s41, 0
	s_add_u32 s42, s42, 0x100
	v_mov_b32_e32 v0, 0
	s_addc_u32 s43, s43, 0
	s_mov_b32 s40, 0
	v_mov_b32_e32 v1, v0
	v_mov_b32_e32 v2, v0
	v_mov_b32_e32 v3, v0
	v_mov_b32_e32 v4, v0
	v_mov_b32_e32 v5, v0
	v_mov_b32_e32 v6, v0
	v_mov_b32_e32 v7, v0
	v_mov_b32_e32 v8, v0
	v_mov_b32_e32 v9, v0
	v_mov_b32_e32 v10, v0
	v_mov_b32_e32 v11, v0
	v_mov_b32_e32 v12, v0
	v_mov_b32_e32 v13, v0
	v_mov_b32_e32 v14, v0
	v_mov_b32_e32 v15, v0
	v_mov_b32_e32 v16, v0
	v_mov_b32_e32 v17, v0
	v_mov_b32_e32 v18, v0
	v_mov_b32_e32 v19, v0
	v_mov_b32_e32 v20, v0
	v_mov_b32_e32 v21, v0
	v_mov_b32_e32 v22, v0
	v_mov_b32_e32 v23, v0
	v_mov_b32_e32 v24, v0
	v_mov_b32_e32 v25, v0
	v_mov_b32_e32 v26, v0
	v_mov_b32_e32 v27, v0
	v_mov_b32_e32 v28, v0
	v_mov_b32_e32 v29, v0
	v_mov_b32_e32 v30, v0
	v_mov_b32_e32 v31, v0
	v_mov_b32_e32 v64, v0
	v_mov_b32_e32 v65, v0
	v_mov_b32_e32 v66, v0
	v_mov_b32_e32 v67, v0
	v_mov_b32_e32 v68, v0
	v_mov_b32_e32 v69, v0
	v_mov_b32_e32 v70, v0
	v_mov_b32_e32 v71, v0
	v_mov_b32_e32 v72, v0
	v_mov_b32_e32 v73, v0
	v_mov_b32_e32 v74, v0
	v_mov_b32_e32 v75, v0
	v_mov_b32_e32 v76, v0
	v_mov_b32_e32 v77, v0
	v_mov_b32_e32 v78, v0
	v_mov_b32_e32 v79, v0
	v_mov_b32_e32 v80, v0
	v_mov_b32_e32 v81, v0
	v_mov_b32_e32 v82, v0
	v_mov_b32_e32 v83, v0
	v_mov_b32_e32 v84, v0
	v_mov_b32_e32 v85, v0
	v_mov_b32_e32 v86, v0
	v_mov_b32_e32 v87, v0
	v_mov_b32_e32 v88, v0
	v_mov_b32_e32 v89, v0
	v_mov_b32_e32 v90, v0
	v_mov_b32_e32 v91, v0
	v_mov_b32_e32 v92, v0
	v_mov_b32_e32 v93, v0
	v_mov_b32_e32 v94, v0
	v_mov_b32_e32 v95, v0
	v_mov_b32_e32 v32, v0
	v_mov_b32_e32 v33, v0
	v_mov_b32_e32 v34, v0
	v_mov_b32_e32 v35, v0
	v_mov_b32_e32 v36, v0
	v_mov_b32_e32 v37, v0
	v_mov_b32_e32 v38, v0
	v_mov_b32_e32 v39, v0
	v_mov_b32_e32 v40, v0
	v_mov_b32_e32 v41, v0
	v_mov_b32_e32 v42, v0
	v_mov_b32_e32 v43, v0
	v_mov_b32_e32 v44, v0
	v_mov_b32_e32 v45, v0
	v_mov_b32_e32 v46, v0
	v_mov_b32_e32 v47, v0
	v_mov_b32_e32 v48, v0
	v_mov_b32_e32 v49, v0
	v_mov_b32_e32 v50, v0
	v_mov_b32_e32 v51, v0
	v_mov_b32_e32 v52, v0
	v_mov_b32_e32 v53, v0
	v_mov_b32_e32 v54, v0
	v_mov_b32_e32 v55, v0
	v_mov_b32_e32 v56, v0
	v_mov_b32_e32 v57, v0
	v_mov_b32_e32 v58, v0
	v_mov_b32_e32 v59, v0
	v_mov_b32_e32 v60, v0
	v_mov_b32_e32 v61, v0
	v_mov_b32_e32 v62, v0
	v_mov_b32_e32 v63, v0
	v_mov_b32_e32 v100, v0
	v_mov_b32_e32 v101, v0
	v_mov_b32_e32 v102, v0
	v_mov_b32_e32 v103, v0
	v_mov_b32_e32 v108, v0
	v_mov_b32_e32 v109, v0
	v_mov_b32_e32 v110, v0
	v_mov_b32_e32 v111, v0
	v_mov_b32_e32 v112, v0
	v_mov_b32_e32 v113, v0
	v_mov_b32_e32 v114, v0
	v_mov_b32_e32 v115, v0
	v_mov_b32_e32 v116, v0
	v_mov_b32_e32 v117, v0
	v_mov_b32_e32 v118, v0
	v_mov_b32_e32 v119, v0
	v_mov_b32_e32 v120, v0
	v_mov_b32_e32 v121, v0
	v_mov_b32_e32 v122, v0
	v_mov_b32_e32 v123, v0
	v_mov_b32_e32 v124, v0
	v_mov_b32_e32 v125, v0
	v_mov_b32_e32 v126, v0
	v_mov_b32_e32 v127, v0
	v_mov_b32_e32 v128, v0
	v_mov_b32_e32 v129, v0
	v_mov_b32_e32 v130, v0
	v_mov_b32_e32 v131, v0
	v_mov_b32_e32 v132, v0
	v_mov_b32_e32 v133, v0
	v_mov_b32_e32 v134, v0
	v_mov_b32_e32 v135, v0

; template <class Epi, class Sched, bool ALIGN_EPI = false, bool SP2 = false>
; __device__ __forceinline__ void gemm_phase(PG8_LAS unsigned char* lds, const Gemm g, const Sched& S, const Epi& E, int tid_in) {
;     ...
;         for (int t = 0; t < nt; t += 2) {
;     ...
;         for (int a = 0; a < 2; ++a)
; #pragma unroll
;             for (int b = 0; b < 2; ++b)
; #pragma unroll
;                 for (int m = 0; m < 4; ++m)
; #pragma unroll
;                     for (int n = 0; n < 2; ++n) acc[a][b][m][n] = (f32x4){0.f, 0.f, 0.f, 0.f};
.LBB0_1242:
	s_andn2_b64 vcc, exec, s[16:17]
	s_cbranch_vccz .Lkeep_acc_4
	v_mov_b32_e32 v123, 0
	v_mov_b32_e32 v122, v123
	v_mov_b32_e32 v121, v123
	v_mov_b32_e32 v120, v123
	v_mov_b32_e32 v127, v123
	v_mov_b32_e32 v126, v123
	v_mov_b32_e32 v125, v123
	v_mov_b32_e32 v124, v123
	v_mov_b32_e32 v111, v123
	v_mov_b32_e32 v110, v123
	v_mov_b32_e32 v109, v123
	v_mov_b32_e32 v108, v123
	v_mov_b32_e32 v107, v123
	v_mov_b32_e32 v106, v123
	v_mov_b32_e32 v105, v123
	v_mov_b32_e32 v104, v123
	v_mov_b32_e32 v95, v123
	v_mov_b32_e32 v94, v123
	v_mov_b32_e32 v93, v123
	v_mov_b32_e32 v92, v123
	v_mov_b32_e32 v91, v123
	v_mov_b32_e32 v90, v123
	v_mov_b32_e32 v89, v123
	v_mov_b32_e32 v88, v123
	v_mov_b32_e32 v79, v123
	v_mov_b32_e32 v78, v123
	v_mov_b32_e32 v77, v123
	v_mov_b32_e32 v76, v123
	v_mov_b32_e32 v75, v123
	v_mov_b32_e32 v74, v123
	v_mov_b32_e32 v73, v123
	v_mov_b32_e32 v72, v123
	v_mov_b32_e32 v119, v123
	v_mov_b32_e32 v118, v123
	v_mov_b32_e32 v117, v123
	v_mov_b32_e32 v116, v123
	v_mov_b32_e32 v115, v123
	v_mov_b32_e32 v114, v123
	v_mov_b32_e32 v113, v123
	v_mov_b32_e32 v112, v123
	v_mov_b32_e32 v103, v123
	v_mov_b32_e32 v102, v123
	v_mov_b32_e32 v101, v123
	v_mov_b32_e32 v100, v123
	v_mov_b32_e32 v99, v123
	v_mov_b32_e32 v98, v123
	v_mov_b32_e32 v97, v123
	v_mov_b32_e32 v96, v123
	v_mov_b32_e32 v87, v123
	v_mov_b32_e32 v86, v123
	v_mov_b32_e32 v85, v123
	v_mov_b32_e32 v84, v123
	v_mov_b32_e32 v83, v123
	v_mov_b32_e32 v82, v123
	v_mov_b32_e32 v81, v123
	v_mov_b32_e32 v80, v123
	v_mov_b32_e32 v71, v123
	v_mov_b32_e32 v70, v123
	v_mov_b32_e32 v69, v123
	v_mov_b32_e32 v68, v123
	v_mov_b32_e32 v67, v123
	v_mov_b32_e32 v66, v123
	v_mov_b32_e32 v65, v123
	v_mov_b32_e32 v64, v123
	v_mov_b32_e32 v63, v123
	v_mov_b32_e32 v62, v123
	v_mov_b32_e32 v61, v123
	v_mov_b32_e32 v60, v123
	v_mov_b32_e32 v59, v123
	v_mov_b32_e32 v58, v123
	v_mov_b32_e32 v57, v123
	v_mov_b32_e32 v56, v123
	v_mov_b32_e32 v47, v123
	v_mov_b32_e32 v46, v123
	v_mov_b32_e32 v45, v123
	v_mov_b32_e32 v44, v123
	v_mov_b32_e32 v43, v123
	v_mov_b32_e32 v42, v123
	v_mov_b32_e32 v41, v123
	v_mov_b32_e32 v40, v123
	v_mov_b32_e32 v31, v123
	v_mov_b32_e32 v30, v123
	v_mov_b32_e32 v29, v123
	v_mov_b32_e32 v28, v123
	v_mov_b32_e32 v27, v123
	v_mov_b32_e32 v26, v123
	v_mov_b32_e32 v25, v123
	v_mov_b32_e32 v24, v123
	v_mov_b32_e32 v15, v123
	v_mov_b32_e32 v14, v123
	v_mov_b32_e32 v13, v123
	v_mov_b32_e32 v12, v123
	v_mov_b32_e32 v11, v123
	v_mov_b32_e32 v10, v123
	v_mov_b32_e32 v9, v123
	v_mov_b32_e32 v8, v123
	v_mov_b32_e32 v55, v123
	v_mov_b32_e32 v54, v123
	v_mov_b32_e32 v53, v123
	v_mov_b32_e32 v52, v123
	v_mov_b32_e32 v51, v123
	v_mov_b32_e32 v50, v123
	v_mov_b32_e32 v49, v123
	v_mov_b32_e32 v48, v123
	v_mov_b32_e32 v39, v123
	v_mov_b32_e32 v38, v123
	v_mov_b32_e32 v37, v123
	v_mov_b32_e32 v36, v123
	v_mov_b32_e32 v35, v123
	v_mov_b32_e32 v34, v123
	v_mov_b32_e32 v33, v123
	v_mov_b32_e32 v32, v123
	v_mov_b32_e32 v23, v123
	v_mov_b32_e32 v22, v123
	v_mov_b32_e32 v21, v123
	v_mov_b32_e32 v20, v123
	v_mov_b32_e32 v19, v123
	v_mov_b32_e32 v18, v123
	v_mov_b32_e32 v17, v123
	v_mov_b32_e32 v16, v123
	v_mov_b32_e32 v7, v123
	v_mov_b32_e32 v6, v123
	v_mov_b32_e32 v5, v123
	v_mov_b32_e32 v4, v123
	v_mov_b32_e32 v3, v123
	v_mov_b32_e32 v2, v123
	v_mov_b32_e32 v1, v123
	v_mov_b32_e32 v0, v123
	s_branch .LBB0_1245
.Lkeep_acc_4:
	s_add_u32 s36, s36, 0x80
	s_addc_u32 s37, s37, 0
	s_add_u32 s33, s38, 0x100
	v_mov_b32_e32 v0, 0
	s_addc_u32 s79, s39, 0
	s_mov_b32 s38, 0
	v_mov_b32_e32 v1, v0
	v_mov_b32_e32 v2, v0
	v_mov_b32_e32 v3, v0
	v_mov_b32_e32 v4, v0
	v_mov_b32_e32 v5, v0
	v_mov_b32_e32 v6, v0
	v_mov_b32_e32 v7, v0
	v_mov_b32_e32 v16, v0
	v_mov_b32_e32 v17, v0
	v_mov_b32_e32 v18, v0
	v_mov_b32_e32 v19, v0
	v_mov_b32_e32 v20, v0
	v_mov_b32_e32 v21, v0
	v_mov_b32_e32 v22, v0
	v_mov_b32_e32 v23, v0
	v_mov_b32_e32 v32, v0
	v_mov_b32_e32 v33, v0
	v_mov_b32_e32 v34, v0
	v_mov_b32_e32 v35, v0
	v_mov_b32_e32 v36, v0
	v_mov_b32_e32 v37, v0
	v_mov_b32_e32 v38, v0
	v_mov_b32_e32 v39, v0
	v_mov_b32_e32 v48, v0
	v_mov_b32_e32 v49, v0
	v_mov_b32_e32 v50, v0
	v_mov_b32_e32 v51, v0
	v_mov_b32_e32 v52, v0
	v_mov_b32_e32 v53, v0
	v_mov_b32_e32 v54, v0
	v_mov_b32_e32 v55, v0
	v_mov_b32_e32 v8, v0
	v_mov_b32_e32 v9, v0
	v_mov_b32_e32 v10, v0
	v_mov_b32_e32 v11, v0
	v_mov_b32_e32 v12, v0
	v_mov_b32_e32 v13, v0
	v_mov_b32_e32 v14, v0
	v_mov_b32_e32 v15, v0
	v_mov_b32_e32 v24, v0
	v_mov_b32_e32 v25, v0
	v_mov_b32_e32 v26, v0
	v_mov_b32_e32 v27, v0
	v_mov_b32_e32 v28, v0
	v_mov_b32_e32 v29, v0
	v_mov_b32_e32 v30, v0
	v_mov_b32_e32 v31, v0
	v_mov_b32_e32 v40, v0
	v_mov_b32_e32 v41, v0
	v_mov_b32_e32 v42, v0
	v_mov_b32_e32 v43, v0
	v_mov_b32_e32 v44, v0
	v_mov_b32_e32 v45, v0
	v_mov_b32_e32 v46, v0
	v_mov_b32_e32 v47, v0
	v_mov_b32_e32 v56, v0
	v_mov_b32_e32 v57, v0
	v_mov_b32_e32 v58, v0
	v_mov_b32_e32 v59, v0
	v_mov_b32_e32 v60, v0
	v_mov_b32_e32 v61, v0
	v_mov_b32_e32 v62, v0
	v_mov_b32_e32 v63, v0
	v_mov_b32_e32 v64, v0
	v_mov_b32_e32 v65, v0
	v_mov_b32_e32 v66, v0
	v_mov_b32_e32 v67, v0
	v_mov_b32_e32 v68, v0
	v_mov_b32_e32 v69, v0
	v_mov_b32_e32 v70, v0
	v_mov_b32_e32 v71, v0
	v_mov_b32_e32 v80, v0
	v_mov_b32_e32 v81, v0
	v_mov_b32_e32 v82, v0
	v_mov_b32_e32 v83, v0
	v_mov_b32_e32 v84, v0
	v_mov_b32_e32 v85, v0
	v_mov_b32_e32 v86, v0
	v_mov_b32_e32 v87, v0
	v_mov_b32_e32 v96, v0
	v_mov_b32_e32 v97, v0
	v_mov_b32_e32 v98, v0
	v_mov_b32_e32 v99, v0
	v_mov_b32_e32 v100, v0
	v_mov_b32_e32 v101, v0
	v_mov_b32_e32 v102, v0
	v_mov_b32_e32 v103, v0
	v_mov_b32_e32 v112, v0
	v_mov_b32_e32 v113, v0
	v_mov_b32_e32 v114, v0
	v_mov_b32_e32 v115, v0
	v_mov_b32_e32 v116, v0
	v_mov_b32_e32 v117, v0
	v_mov_b32_e32 v118, v0
	v_mov_b32_e32 v119, v0
	v_mov_b32_e32 v72, v0
	v_mov_b32_e32 v73, v0
	v_mov_b32_e32 v74, v0
	v_mov_b32_e32 v75, v0
	v_mov_b32_e32 v76, v0
	v_mov_b32_e32 v77, v0
	v_mov_b32_e32 v78, v0
	v_mov_b32_e32 v79, v0
	v_mov_b32_e32 v88, v0
	v_mov_b32_e32 v89, v0
	v_mov_b32_e32 v90, v0
	v_mov_b32_e32 v91, v0
	v_mov_b32_e32 v92, v0
	v_mov_b32_e32 v93, v0
	v_mov_b32_e32 v94, v0
	v_mov_b32_e32 v95, v0
	v_mov_b32_e32 v104, v0
	v_mov_b32_e32 v105, v0
	v_mov_b32_e32 v106, v0
	v_mov_b32_e32 v107, v0
	v_mov_b32_e32 v108, v0
	v_mov_b32_e32 v109, v0
	v_mov_b32_e32 v110, v0
	v_mov_b32_e32 v111, v0
	v_mov_b32_e32 v124, v0
	v_mov_b32_e32 v125, v0
	v_mov_b32_e32 v126, v0
	v_mov_b32_e32 v127, v0
	v_mov_b32_e32 v120, v0
	v_mov_b32_e32 v121, v0
	v_mov_b32_e32 v122, v0
	v_mov_b32_e32 v123, v0

; template <class Epi, class Sched, bool ALIGN_EPI = false, bool SP2 = false>
; __device__ __forceinline__ void gemm_phase(PG8_LAS unsigned char* lds, const Gemm g, const Sched& S, const Epi& E, int tid_in) {
;     ...
;         for (int t = 0; t < nt; t += 2) {
;     ...
;         for (int a = 0; a < 2; ++a)
; #pragma unroll
;             for (int b = 0; b < 2; ++b)
; #pragma unroll
;                 for (int m = 0; m < 4; ++m)
; #pragma unroll
;                     for (int n = 0; n < 2; ++n) acc[a][b][m][n] = (f32x4){0.f, 0.f, 0.f, 0.f};
.LBB0_1580:
	s_andn2_b64 vcc, exec, s[22:23]
	s_cbranch_vccz .Lkeep_acc_5
	v_mov_b32_e32 v123, 0
	v_mov_b32_e32 v122, v123
	v_mov_b32_e32 v121, v123
	v_mov_b32_e32 v120, v123
	v_mov_b32_e32 v127, v123
	v_mov_b32_e32 v126, v123
	v_mov_b32_e32 v125, v123
	v_mov_b32_e32 v124, v123
	v_mov_b32_e32 v111, v123
	v_mov_b32_e32 v110, v123
	v_mov_b32_e32 v109, v123
	v_mov_b32_e32 v108, v123
	v_mov_b32_e32 v107, v123
	v_mov_b32_e32 v106, v123
	v_mov_b32_e32 v105, v123
	v_mov_b32_e32 v104, v123
	v_mov_b32_e32 v95, v123
	v_mov_b32_e32 v94, v123
	v_mov_b32_e32 v93, v123
	v_mov_b32_e32 v92, v123
	v_mov_b32_e32 v91, v123
	v_mov_b32_e32 v90, v123
	v_mov_b32_e32 v89, v123
	v_mov_b32_e32 v88, v123
	v_mov_b32_e32 v79, v123
	v_mov_b32_e32 v78, v123
	v_mov_b32_e32 v77, v123
	v_mov_b32_e32 v76, v123
	v_mov_b32_e32 v75, v123
	v_mov_b32_e32 v74, v123
	v_mov_b32_e32 v73, v123
	v_mov_b32_e32 v72, v123
	v_mov_b32_e32 v119, v123
	v_mov_b32_e32 v118, v123
	v_mov_b32_e32 v117, v123
	v_mov_b32_e32 v116, v123
	v_mov_b32_e32 v115, v123
	v_mov_b32_e32 v114, v123
	v_mov_b32_e32 v113, v123
	v_mov_b32_e32 v112, v123
	v_mov_b32_e32 v103, v123
	v_mov_b32_e32 v102, v123
	v_mov_b32_e32 v101, v123
	v_mov_b32_e32 v100, v123
	v_mov_b32_e32 v99, v123
	v_mov_b32_e32 v98, v123
	v_mov_b32_e32 v97, v123
	v_mov_b32_e32 v96, v123
	v_mov_b32_e32 v87, v123
	v_mov_b32_e32 v86, v123
	v_mov_b32_e32 v85, v123
	v_mov_b32_e32 v84, v123
	v_mov_b32_e32 v83, v123
	v_mov_b32_e32 v82, v123
	v_mov_b32_e32 v81, v123
	v_mov_b32_e32 v80, v123
	v_mov_b32_e32 v71, v123
	v_mov_b32_e32 v70, v123
	v_mov_b32_e32 v69, v123
	v_mov_b32_e32 v68, v123
	v_mov_b32_e32 v67, v123
	v_mov_b32_e32 v66, v123
	v_mov_b32_e32 v65, v123
	v_mov_b32_e32 v64, v123
	v_mov_b32_e32 v63, v123
	v_mov_b32_e32 v62, v123
	v_mov_b32_e32 v61, v123
	v_mov_b32_e32 v60, v123
	v_mov_b32_e32 v59, v123
	v_mov_b32_e32 v58, v123
	v_mov_b32_e32 v57, v123
	v_mov_b32_e32 v56, v123
	v_mov_b32_e32 v47, v123
	v_mov_b32_e32 v46, v123
	v_mov_b32_e32 v45, v123
	v_mov_b32_e32 v44, v123
	v_mov_b32_e32 v43, v123
	v_mov_b32_e32 v42, v123
	v_mov_b32_e32 v41, v123
	v_mov_b32_e32 v40, v123
	v_mov_b32_e32 v31, v123
	v_mov_b32_e32 v30, v123
	v_mov_b32_e32 v29, v123
	v_mov_b32_e32 v28, v123
	v_mov_b32_e32 v27, v123
	v_mov_b32_e32 v26, v123
	v_mov_b32_e32 v25, v123
	v_mov_b32_e32 v24, v123
	v_mov_b32_e32 v15, v123
	v_mov_b32_e32 v14, v123
	v_mov_b32_e32 v13, v123
	v_mov_b32_e32 v12, v123
	v_mov_b32_e32 v11, v123
	v_mov_b32_e32 v10, v123
	v_mov_b32_e32 v9, v123
	v_mov_b32_e32 v8, v123
	v_mov_b32_e32 v55, v123
	v_mov_b32_e32 v54, v123
	v_mov_b32_e32 v53, v123
	v_mov_b32_e32 v52, v123
	v_mov_b32_e32 v51, v123
	v_mov_b32_e32 v50, v123
	v_mov_b32_e32 v49, v123
	v_mov_b32_e32 v48, v123
	v_mov_b32_e32 v39, v123
	v_mov_b32_e32 v38, v123
	v_mov_b32_e32 v37, v123
	v_mov_b32_e32 v36, v123
	v_mov_b32_e32 v35, v123
	v_mov_b32_e32 v34, v123
	v_mov_b32_e32 v33, v123
	v_mov_b32_e32 v32, v123
	v_mov_b32_e32 v23, v123
	v_mov_b32_e32 v22, v123
	v_mov_b32_e32 v21, v123
	v_mov_b32_e32 v20, v123
	v_mov_b32_e32 v19, v123
	v_mov_b32_e32 v18, v123
	v_mov_b32_e32 v17, v123
	v_mov_b32_e32 v16, v123
	v_mov_b32_e32 v7, v123
	v_mov_b32_e32 v6, v123
	v_mov_b32_e32 v5, v123
	v_mov_b32_e32 v4, v123
	v_mov_b32_e32 v3, v123
	v_mov_b32_e32 v2, v123
	v_mov_b32_e32 v1, v123
	v_mov_b32_e32 v0, v123
	s_branch .LBB0_1583
.Lkeep_acc_5:
	s_add_u32 s38, s38, 0x80
	s_addc_u32 s39, s39, 0
	s_add_u32 s33, s40, 0x100
	v_mov_b32_e32 v0, 0
	s_addc_u32 s80, s41, 0
	s_mov_b32 s40, 0
	v_mov_b32_e32 v1, v0
	v_mov_b32_e32 v2, v0
	v_mov_b32_e32 v3, v0
	v_mov_b32_e32 v4, v0
	v_mov_b32_e32 v5, v0
	v_mov_b32_e32 v6, v0
	v_mov_b32_e32 v7, v0
	v_mov_b32_e32 v16, v0
	v_mov_b32_e32 v17, v0
	v_mov_b32_e32 v18, v0
	v_mov_b32_e32 v19, v0
	v_mov_b32_e32 v20, v0
	v_mov_b32_e32 v21, v0
	v_mov_b32_e32 v22, v0
	v_mov_b32_e32 v23, v0
	v_mov_b32_e32 v32, v0
	v_mov_b32_e32 v33, v0
	v_mov_b32_e32 v34, v0
	v_mov_b32_e32 v35, v0
	v_mov_b32_e32 v36, v0
	v_mov_b32_e32 v37, v0
	v_mov_b32_e32 v38, v0
	v_mov_b32_e32 v39, v0
	v_mov_b32_e32 v48, v0
	v_mov_b32_e32 v49, v0
	v_mov_b32_e32 v50, v0
	v_mov_b32_e32 v51, v0
	v_mov_b32_e32 v52, v0
	v_mov_b32_e32 v53, v0
	v_mov_b32_e32 v54, v0
	v_mov_b32_e32 v55, v0
	v_mov_b32_e32 v8, v0
	v_mov_b32_e32 v9, v0
	v_mov_b32_e32 v10, v0
	v_mov_b32_e32 v11, v0
	v_mov_b32_e32 v12, v0
	v_mov_b32_e32 v13, v0
	v_mov_b32_e32 v14, v0
	v_mov_b32_e32 v15, v0
	v_mov_b32_e32 v24, v0
	v_mov_b32_e32 v25, v0
	v_mov_b32_e32 v26, v0
	v_mov_b32_e32 v27, v0
	v_mov_b32_e32 v28, v0
	v_mov_b32_e32 v29, v0
	v_mov_b32_e32 v30, v0
	v_mov_b32_e32 v31, v0
	v_mov_b32_e32 v40, v0
	v_mov_b32_e32 v41, v0
	v_mov_b32_e32 v42, v0
	v_mov_b32_e32 v43, v0
	v_mov_b32_e32 v44, v0
	v_mov_b32_e32 v45, v0
	v_mov_b32_e32 v46, v0
	v_mov_b32_e32 v47, v0
	v_mov_b32_e32 v56, v0
	v_mov_b32_e32 v57, v0
	v_mov_b32_e32 v58, v0
	v_mov_b32_e32 v59, v0
	v_mov_b32_e32 v60, v0
	v_mov_b32_e32 v61, v0
	v_mov_b32_e32 v62, v0
	v_mov_b32_e32 v63, v0
	v_mov_b32_e32 v64, v0
	v_mov_b32_e32 v65, v0
	v_mov_b32_e32 v66, v0
	v_mov_b32_e32 v67, v0
	v_mov_b32_e32 v68, v0
	v_mov_b32_e32 v69, v0
	v_mov_b32_e32 v70, v0
	v_mov_b32_e32 v71, v0
	v_mov_b32_e32 v80, v0
	v_mov_b32_e32 v81, v0
	v_mov_b32_e32 v82, v0
	v_mov_b32_e32 v83, v0
	v_mov_b32_e32 v84, v0
	v_mov_b32_e32 v85, v0
	v_mov_b32_e32 v86, v0
	v_mov_b32_e32 v87, v0
	v_mov_b32_e32 v96, v0
	v_mov_b32_e32 v97, v0
	v_mov_b32_e32 v98, v0
	v_mov_b32_e32 v99, v0
	v_mov_b32_e32 v100, v0
	v_mov_b32_e32 v101, v0
	v_mov_b32_e32 v102, v0
	v_mov_b32_e32 v103, v0
	v_mov_b32_e32 v112, v0
	v_mov_b32_e32 v113, v0
	v_mov_b32_e32 v114, v0
	v_mov_b32_e32 v115, v0
	v_mov_b32_e32 v116, v0
	v_mov_b32_e32 v117, v0
	v_mov_b32_e32 v118, v0
	v_mov_b32_e32 v119, v0
	v_mov_b32_e32 v72, v0
	v_mov_b32_e32 v73, v0
	v_mov_b32_e32 v74, v0
	v_mov_b32_e32 v75, v0
	v_mov_b32_e32 v76, v0
	v_mov_b32_e32 v77, v0
	v_mov_b32_e32 v78, v0
	v_mov_b32_e32 v79, v0
	v_mov_b32_e32 v88, v0
	v_mov_b32_e32 v89, v0
	v_mov_b32_e32 v90, v0
	v_mov_b32_e32 v91, v0
	v_mov_b32_e32 v92, v0
	v_mov_b32_e32 v93, v0
	v_mov_b32_e32 v94, v0
	v_mov_b32_e32 v95, v0
	v_mov_b32_e32 v104, v0
	v_mov_b32_e32 v105, v0
	v_mov_b32_e32 v106, v0
	v_mov_b32_e32 v107, v0
	v_mov_b32_e32 v108, v0
	v_mov_b32_e32 v109, v0
	v_mov_b32_e32 v110, v0
	v_mov_b32_e32 v111, v0
	v_mov_b32_e32 v124, v0
	v_mov_b32_e32 v125, v0
	v_mov_b32_e32 v126, v0
	v_mov_b32_e32 v127, v0
	v_mov_b32_e32 v120, v0
	v_mov_b32_e32 v121, v0
	v_mov_b32_e32 v122, v0
	v_mov_b32_e32 v123, v0
